# SSM carry scan: E values read 8 chunks ahead, immediate-offset stores, same per-step math order
# speedup vs baseline: 1.0151x; 1.0016x over previous
.LBB0_602:
	v_lshlrev_b32_e32 v1, 5, v60
	v_lshlrev_b32_e32 v34, 2, v62
	v_lshl_or_b32 v1, v61, 2, v1
	v_lshl_or_b32 v34, v59, 8, v34
	s_movk_i32 s0, 0x204
	v_mad_u64_u32 v[34:35], s[0:1], v1, s0, v[34:35]
	v_add_u32_e32 v1, 0x400, v34
	s_waitcnt vmcnt(0)
	s_barrier
	ds_write2_b32 v34, v2, v18 offset1:32
	ds_write2_b32 v34, v3, v19 offset0:129 offset1:161
	ds_write2_b32 v1, v4, v20 offset0:2 offset1:34
	ds_write2_b32 v1, v5, v21 offset0:131 offset1:163
	v_add_u32_e32 v1, 0x1000, v34
	ds_write2_b32 v1, v6, v22 offset0:8 offset1:40
	ds_write2_b32 v1, v7, v23 offset0:137 offset1:169
	v_add_u32_e32 v1, 0x1400, v34
	ds_write2_b32 v1, v8, v24 offset0:10 offset1:42
	ds_write2_b32 v1, v9, v25 offset0:139 offset1:171
	v_add_u32_e32 v1, 0x2000, v34
	ds_write2_b32 v1, v10, v26 offset0:16 offset1:48
	ds_write2_b32 v1, v11, v27 offset0:145 offset1:177
	v_add_u32_e32 v1, 0x2400, v34
	ds_write2_b32 v1, v12, v28 offset0:18 offset1:50
	ds_write2_b32 v1, v13, v29 offset0:147 offset1:179
	v_add_u32_e32 v1, 0x3000, v34
	ds_write2_b32 v1, v14, v30 offset0:24 offset1:56
	ds_write2_b32 v1, v15, v31 offset0:153 offset1:185
	v_add_u32_e32 v1, 0x3400, v34
	v_mov_b32_e32 v2, v194
	ds_write2_b32 v1, v16, v32 offset0:26 offset1:58
	ds_write2_b32 v1, v17, v33 offset0:155 offset1:187
	s_waitcnt lgkmcnt(0)
	s_barrier
	s_barrier
	s_nop 0
	v_cmp_gt_i32_e32 vcc, 64, v2
	s_and_saveexec_b64 s[0:1], vcc
	s_cbranch_execz .LBB0_534
	s_lshl_b32 s7, s7, 6
	v_readlane_b32 s8, v229, 49
	s_or_b32 s7, s7, s8
	v_add_lshl_u32 v4, s7, v2, 1
	v_ashrrev_i32_e32 v5, 31, v4
	v_lshl_add_u64 v[4:5], v[4:5], 2, s[84:85]
	global_load_dwordx2 v[4:5], v[4:5], off
	s_ashr_i32 s7, s6, 31
	v_readlane_b32 s12, v230, 7
	s_lshl_b64 s[4:5], s[4:5], 15
	s_lshl_b64 s[6:7], s[6:7], 15
	v_readlane_b32 s18, v230, 13
	v_readlane_b32 s19, v230, 14
	s_add_u32 s4, s18, s4
	s_addc_u32 s5, s19, s5
	s_add_u32 s6, s18, s6
	s_movk_i32 s8, 0x204
	v_ashrrev_i32_e32 v3, 31, v2
	v_mov_b32_e32 v10, 0
	s_addc_u32 s7, s19, s7
	v_mul_lo_u32 v1, v2, s8
	s_mov_b32 s8, 0
	v_lshl_add_u64 v[6:7], v[2:3], 1, s[6:7]
	v_mov_b32_e32 v11, v10
	v_readlane_b32 s13, v230, 8
	v_readlane_b32 s14, v230, 9
	v_readlane_b32 s15, v230, 10
	v_readlane_b32 s16, v230, 11
	v_readlane_b32 s17, v230, 12
	s_waitcnt vmcnt(0)
	v_pk_mov_b32 v[8:9], v[4:5], v[4:5] op_sel:[1,0]
	v_add_u32_e32 v3, 0x8100, v1
	v_add_u32_e32 v12, 64, v2
	v_mov_b32_e32 v13, 0
	v_lshl_add_u64 v[12:13], v[12:13], 1, s[4:5]
	s_mov_b64 s[6:7], 0x1000
	s_mov_b32 s8, 8
	ds_read2_b32 v[22:23], v1 offset0:0 offset1:1
	ds_read2_b32 v[24:25], v1 offset0:2 offset1:3
	ds_read2_b32 v[26:27], v1 offset0:4 offset1:5
	ds_read2_b32 v[28:29], v1 offset0:6 offset1:7
	ds_read2_b32 v[30:31], v3 offset0:0 offset1:1
	ds_read2_b32 v[32:33], v3 offset0:2 offset1:3
	ds_read2_b32 v[34:35], v3 offset0:4 offset1:5
	ds_read2_b32 v[36:37], v3 offset0:6 offset1:7
.Lscan_loop:
	ds_read2_b32 v[38:39], v1 offset0:8 offset1:9
	ds_read2_b32 v[40:41], v1 offset0:10 offset1:11
	ds_read2_b32 v[42:43], v1 offset0:12 offset1:13
	ds_read2_b32 v[44:45], v1 offset0:14 offset1:15
	ds_read2_b32 v[46:47], v3 offset0:8 offset1:9
	ds_read2_b32 v[48:49], v3 offset0:10 offset1:11
	ds_read2_b32 v[50:51], v3 offset0:12 offset1:13
	ds_read2_b32 v[52:53], v3 offset0:14 offset1:15
	s_waitcnt lgkmcnt(8)
	v_cvt_pk_bf16_f32 v14, v10, v11
	v_pk_mul_f32 v[16:17], v[8:9], v[10:11] op_sel:[0,1]
	global_store_short v[6:7], v14, off
	v_pk_fma_f32 v[18:19], v[4:5], v[10:11], v[16:17] neg_lo:[0,0,1] neg_hi:[0,0,1]
	v_pk_fma_f32 v[10:11], v[4:5], v[10:11], v[16:17] op_sel_hi:[1,0,1]
	global_store_short_d16_hi v[12:13], v14, off
	v_add_f32_e32 v10, v18, v22
	v_add_f32_e32 v11, v11, v30
	v_cvt_pk_bf16_f32 v15, v10, v11
	v_pk_mul_f32 v[16:17], v[8:9], v[10:11] op_sel:[0,1]
	global_store_short v[6:7], v15, off offset:256
	v_pk_fma_f32 v[18:19], v[4:5], v[10:11], v[16:17] neg_lo:[0,0,1] neg_hi:[0,0,1]
	v_pk_fma_f32 v[10:11], v[4:5], v[10:11], v[16:17] op_sel_hi:[1,0,1]
	global_store_short_d16_hi v[12:13], v15, off offset:256
	v_add_f32_e32 v10, v18, v23
	v_add_f32_e32 v11, v11, v31
	v_cvt_pk_bf16_f32 v14, v10, v11
	v_pk_mul_f32 v[16:17], v[8:9], v[10:11] op_sel:[0,1]
	global_store_short v[6:7], v14, off offset:512
	v_pk_fma_f32 v[18:19], v[4:5], v[10:11], v[16:17] neg_lo:[0,0,1] neg_hi:[0,0,1]
	v_pk_fma_f32 v[10:11], v[4:5], v[10:11], v[16:17] op_sel_hi:[1,0,1]
	global_store_short_d16_hi v[12:13], v14, off offset:512
	v_add_f32_e32 v10, v18, v24
	v_add_f32_e32 v11, v11, v32
	v_cvt_pk_bf16_f32 v15, v10, v11
	v_pk_mul_f32 v[16:17], v[8:9], v[10:11] op_sel:[0,1]
	global_store_short v[6:7], v15, off offset:768
	v_pk_fma_f32 v[18:19], v[4:5], v[10:11], v[16:17] neg_lo:[0,0,1] neg_hi:[0,0,1]
	v_pk_fma_f32 v[10:11], v[4:5], v[10:11], v[16:17] op_sel_hi:[1,0,1]
	global_store_short_d16_hi v[12:13], v15, off offset:768
	v_add_f32_e32 v10, v18, v25
	v_add_f32_e32 v11, v11, v33
	v_cvt_pk_bf16_f32 v14, v10, v11
	v_pk_mul_f32 v[16:17], v[8:9], v[10:11] op_sel:[0,1]
	global_store_short v[6:7], v14, off offset:1024
	v_pk_fma_f32 v[18:19], v[4:5], v[10:11], v[16:17] neg_lo:[0,0,1] neg_hi:[0,0,1]
	v_pk_fma_f32 v[10:11], v[4:5], v[10:11], v[16:17] op_sel_hi:[1,0,1]
	global_store_short_d16_hi v[12:13], v14, off offset:1024
	v_add_f32_e32 v10, v18, v26
	v_add_f32_e32 v11, v11, v34
	v_cvt_pk_bf16_f32 v15, v10, v11
	v_pk_mul_f32 v[16:17], v[8:9], v[10:11] op_sel:[0,1]
	global_store_short v[6:7], v15, off offset:1280
	v_pk_fma_f32 v[18:19], v[4:5], v[10:11], v[16:17] neg_lo:[0,0,1] neg_hi:[0,0,1]
	v_pk_fma_f32 v[10:11], v[4:5], v[10:11], v[16:17] op_sel_hi:[1,0,1]
	global_store_short_d16_hi v[12:13], v15, off offset:1280
	v_add_f32_e32 v10, v18, v27
	v_add_f32_e32 v11, v11, v35
	v_cvt_pk_bf16_f32 v14, v10, v11
	v_pk_mul_f32 v[16:17], v[8:9], v[10:11] op_sel:[0,1]
	global_store_short v[6:7], v14, off offset:1536
	v_pk_fma_f32 v[18:19], v[4:5], v[10:11], v[16:17] neg_lo:[0,0,1] neg_hi:[0,0,1]
	v_pk_fma_f32 v[10:11], v[4:5], v[10:11], v[16:17] op_sel_hi:[1,0,1]
	global_store_short_d16_hi v[12:13], v14, off offset:1536
	v_add_f32_e32 v10, v18, v28
	v_add_f32_e32 v11, v11, v36
	v_cvt_pk_bf16_f32 v15, v10, v11
	v_pk_mul_f32 v[16:17], v[8:9], v[10:11] op_sel:[0,1]
	global_store_short v[6:7], v15, off offset:1792
	v_pk_fma_f32 v[18:19], v[4:5], v[10:11], v[16:17] neg_lo:[0,0,1] neg_hi:[0,0,1]
	v_pk_fma_f32 v[10:11], v[4:5], v[10:11], v[16:17] op_sel_hi:[1,0,1]
	global_store_short_d16_hi v[12:13], v15, off offset:1792
	v_add_f32_e32 v10, v18, v29
	v_add_f32_e32 v11, v11, v37
	ds_read2_b32 v[22:23], v1 offset0:16 offset1:17
	ds_read2_b32 v[24:25], v1 offset0:18 offset1:19
	ds_read2_b32 v[26:27], v1 offset0:20 offset1:21
	ds_read2_b32 v[28:29], v1 offset0:22 offset1:23
	ds_read2_b32 v[30:31], v3 offset0:16 offset1:17
	ds_read2_b32 v[32:33], v3 offset0:18 offset1:19
	ds_read2_b32 v[34:35], v3 offset0:20 offset1:21
	ds_read2_b32 v[36:37], v3 offset0:22 offset1:23
	s_waitcnt lgkmcnt(8)
	v_cvt_pk_bf16_f32 v14, v10, v11
	v_pk_mul_f32 v[16:17], v[8:9], v[10:11] op_sel:[0,1]
	global_store_short v[6:7], v14, off offset:2048
	v_pk_fma_f32 v[18:19], v[4:5], v[10:11], v[16:17] neg_lo:[0,0,1] neg_hi:[0,0,1]
	v_pk_fma_f32 v[10:11], v[4:5], v[10:11], v[16:17] op_sel_hi:[1,0,1]
	global_store_short_d16_hi v[12:13], v14, off offset:2048
	v_add_f32_e32 v10, v18, v38
	v_add_f32_e32 v11, v11, v46
	v_cvt_pk_bf16_f32 v15, v10, v11
	v_pk_mul_f32 v[16:17], v[8:9], v[10:11] op_sel:[0,1]
	global_store_short v[6:7], v15, off offset:2304
	v_pk_fma_f32 v[18:19], v[4:5], v[10:11], v[16:17] neg_lo:[0,0,1] neg_hi:[0,0,1]
	v_pk_fma_f32 v[10:11], v[4:5], v[10:11], v[16:17] op_sel_hi:[1,0,1]
	global_store_short_d16_hi v[12:13], v15, off offset:2304
	v_add_f32_e32 v10, v18, v39
	v_add_f32_e32 v11, v11, v47
	v_cvt_pk_bf16_f32 v14, v10, v11
	v_pk_mul_f32 v[16:17], v[8:9], v[10:11] op_sel:[0,1]
	global_store_short v[6:7], v14, off offset:2560
	v_pk_fma_f32 v[18:19], v[4:5], v[10:11], v[16:17] neg_lo:[0,0,1] neg_hi:[0,0,1]
	v_pk_fma_f32 v[10:11], v[4:5], v[10:11], v[16:17] op_sel_hi:[1,0,1]
	global_store_short_d16_hi v[12:13], v14, off offset:2560
	v_add_f32_e32 v10, v18, v40
	v_add_f32_e32 v11, v11, v48
	v_cvt_pk_bf16_f32 v15, v10, v11
	v_pk_mul_f32 v[16:17], v[8:9], v[10:11] op_sel:[0,1]
	global_store_short v[6:7], v15, off offset:2816
	v_pk_fma_f32 v[18:19], v[4:5], v[10:11], v[16:17] neg_lo:[0,0,1] neg_hi:[0,0,1]
	v_pk_fma_f32 v[10:11], v[4:5], v[10:11], v[16:17] op_sel_hi:[1,0,1]
	global_store_short_d16_hi v[12:13], v15, off offset:2816
	v_add_f32_e32 v10, v18, v41
	v_add_f32_e32 v11, v11, v49
	v_cvt_pk_bf16_f32 v14, v10, v11
	v_pk_mul_f32 v[16:17], v[8:9], v[10:11] op_sel:[0,1]
	global_store_short v[6:7], v14, off offset:3072
	v_pk_fma_f32 v[18:19], v[4:5], v[10:11], v[16:17] neg_lo:[0,0,1] neg_hi:[0,0,1]
	v_pk_fma_f32 v[10:11], v[4:5], v[10:11], v[16:17] op_sel_hi:[1,0,1]
	global_store_short_d16_hi v[12:13], v14, off offset:3072
	v_add_f32_e32 v10, v18, v42
	v_add_f32_e32 v11, v11, v50
	v_cvt_pk_bf16_f32 v15, v10, v11
	v_pk_mul_f32 v[16:17], v[8:9], v[10:11] op_sel:[0,1]
	global_store_short v[6:7], v15, off offset:3328
	v_pk_fma_f32 v[18:19], v[4:5], v[10:11], v[16:17] neg_lo:[0,0,1] neg_hi:[0,0,1]
	v_pk_fma_f32 v[10:11], v[4:5], v[10:11], v[16:17] op_sel_hi:[1,0,1]
	global_store_short_d16_hi v[12:13], v15, off offset:3328
	v_add_f32_e32 v10, v18, v43
	v_add_f32_e32 v11, v11, v51
	v_cvt_pk_bf16_f32 v14, v10, v11
	v_pk_mul_f32 v[16:17], v[8:9], v[10:11] op_sel:[0,1]
	global_store_short v[6:7], v14, off offset:3584
	v_pk_fma_f32 v[18:19], v[4:5], v[10:11], v[16:17] neg_lo:[0,0,1] neg_hi:[0,0,1]
	v_pk_fma_f32 v[10:11], v[4:5], v[10:11], v[16:17] op_sel_hi:[1,0,1]
	global_store_short_d16_hi v[12:13], v14, off offset:3584
	v_add_f32_e32 v10, v18, v44
	v_add_f32_e32 v11, v11, v52
	v_cvt_pk_bf16_f32 v15, v10, v11
	v_pk_mul_f32 v[16:17], v[8:9], v[10:11] op_sel:[0,1]
	global_store_short v[6:7], v15, off offset:3840
	v_pk_fma_f32 v[18:19], v[4:5], v[10:11], v[16:17] neg_lo:[0,0,1] neg_hi:[0,0,1]
	v_pk_fma_f32 v[10:11], v[4:5], v[10:11], v[16:17] op_sel_hi:[1,0,1]
	global_store_short_d16_hi v[12:13], v15, off offset:3840
	v_add_f32_e32 v10, v18, v45
	v_add_f32_e32 v11, v11, v53
	v_add_u32_e32 v1, 64, v1
	v_add_u32_e32 v3, 64, v3
	v_lshl_add_u64 v[6:7], v[6:7], 0, s[6:7]
	v_lshl_add_u64 v[12:13], v[12:13], 0, s[6:7]
	s_sub_i32 s8, s8, 1
	s_cmp_lg_u32 s8, 0
	s_cbranch_scc1 .Lscan_loop
	s_waitcnt lgkmcnt(0)
	s_branch .LBB0_534

.LBB0_941:
	s_or_b64 exec, exec, s[0:1]
	v_readlane_b32 s0, v229, 12
	v_readlane_b32 s1, v229, 13
	s_andn2_b64 vcc, exec, s[0:1]
	s_waitcnt lgkmcnt(0)
	s_barrier
	s_cbranch_vccnz .LBB0_964
	v_readlane_b32 s0, v229, 47
	v_readlane_b32 s1, v229, 48
	s_lshl_b32 s22, s0, 11
	s_mov_b32 s2, s0
	s_lshl_b64 s[0:1], s[22:23], 2
	s_add_u32 s4, s42, s0
	s_addc_u32 s5, s43, s1
	s_cmp_lg_u32 s2, 3
	s_cselect_b64 s[6:7], -1, 0
	v_readlane_b32 s2, v229, 23
	v_readlane_b32 s8, v230, 0
	v_and_b32_e32 v170, 63, v194
	v_lshlrev_b32_e32 v170, 5, v170
	v_add_u32_e32 v171, 0x1000, v170
	global_load_dwordx4 v[136:139], v170, s[4:5]
	global_load_dwordx4 v[140:143], v170, s[4:5] offset:16
	global_load_dwordx4 v[144:147], v170, s[4:5] offset:2048
	global_load_dwordx4 v[148:151], v170, s[4:5] offset:2064
	global_load_dwordx4 v[152:155], v171, s[4:5]
	global_load_dwordx4 v[156:159], v171, s[4:5] offset:16
	global_load_dwordx4 v[160:163], v171, s[4:5] offset:2048
	global_load_dwordx4 v[164:167], v171, s[4:5] offset:2064
	s_mov_b32 s78, 1
	s_lshl_b32 s80, s40, 12
	s_mov_b32 s81, 0
	s_branch .LBB0_945

.LBB0_945:
	v_mov_b32_e32 v1, v194
	v_mov_b32_e32 v7, v0
	v_ashrrev_i32_e32 v1, 6, v1
	v_add_u32_e32 v22, s2, v1
	v_mov_b32_e32 v1, v194
	v_ashrrev_i32_e32 v23, 31, v22
	v_and_b32_e32 v1, 63, v1
	s_waitcnt lgkmcnt(0)
	v_lshlrev_b64 v[2:3], 12, v[22:23]
	v_lshl_add_u64 v[4:5], s[98:99], 0, v[2:3]
	v_lshlrev_b32_e32 v6, 4, v1
	v_lshl_add_u64 v[4:5], v[4:5], 0, v[6:7]
	v_mov_b32_e32 v168, v4
	v_mov_b32_e32 v169, v5
	v_and_b32_e32 v4, 64, v203
	v_readlane_b32 s0, v230, 1
	v_xor_b32_e32 v5, 32, v203
	v_add_u32_e32 v100, 64, v4
	v_lshlrev_b32_e32 v54, 5, v1
	v_readlane_b32 s1, v230, 2
	v_cmp_lt_i32_e32 vcc, v5, v100
	v_lshl_add_u64 v[2:3], s[0:1], 0, v[2:3]
	v_cndmask_b32_e32 v4, v203, v5, vcc
	v_lshl_add_u64 v[24:25], v[2:3], 0, v[6:7]
	v_lshlrev_b32_e32 v58, 2, v4
	s_cmp_eq_u32 s78, 0
	s_cbranch_scc1 .Lp7_have
	global_load_dwordx4 v[104:107], v[168:169], off
	global_load_dwordx4 v[108:111], v[168:169], off offset:1024
	global_load_dwordx4 v[112:115], v[168:169], off offset:2048
	global_load_dwordx4 v[116:119], v[168:169], off offset:3072
	global_load_dwordx4 v[120:123], v[24:25], off
	global_load_dwordx4 v[124:127], v[24:25], off offset:1024
	global_load_dwordx4 v[128:131], v[24:25], off offset:2048
	global_load_dwordx4 v[132:135], v[24:25], off offset:3072
	s_mov_b32 s78, 0
	s_waitcnt vmcnt(0)
	s_branch .Lp7_mov

.Lp7_mov:
	v_mov_b32_e32 v14, v104
	v_mov_b32_e32 v15, v105
	v_mov_b32_e32 v16, v106
	v_mov_b32_e32 v17, v107
	v_mov_b32_e32 v18, v108
	v_mov_b32_e32 v19, v109
	v_mov_b32_e32 v20, v110
	v_mov_b32_e32 v21, v111
	v_mov_b32_e32 v26, v112
	v_mov_b32_e32 v27, v113
	v_mov_b32_e32 v28, v114
	v_mov_b32_e32 v29, v115
	v_mov_b32_e32 v42, v116
	v_mov_b32_e32 v43, v117
	v_mov_b32_e32 v44, v118
	v_mov_b32_e32 v45, v119
	v_mov_b32_e32 v72, v120
	v_mov_b32_e32 v73, v121
	v_mov_b32_e32 v74, v122
	v_mov_b32_e32 v75, v123
	v_mov_b32_e32 v10, v124
	v_mov_b32_e32 v11, v125
	v_mov_b32_e32 v12, v126
	v_mov_b32_e32 v13, v127
	v_mov_b32_e32 v6, v128
	v_mov_b32_e32 v7, v129
	v_mov_b32_e32 v8, v130
	v_mov_b32_e32 v9, v131
	v_mov_b32_e32 v2, v132
	v_mov_b32_e32 v3, v133
	v_mov_b32_e32 v4, v134
	v_mov_b32_e32 v5, v135
	s_add_i32 vcc_lo, s8, s34
	s_cmpk_gt_i32 vcc_lo, 0x7ff
	s_cbranch_scc1 .Lp7_nopf
	v_lshl_add_u64 v[168:169], v[168:169], 0, s[80:81]
	v_lshl_add_u64 v[170:171], v[24:25], 0, s[80:81]
	global_load_dwordx4 v[104:107], v[168:169], off
	global_load_dwordx4 v[108:111], v[168:169], off offset:1024
	global_load_dwordx4 v[112:115], v[168:169], off offset:2048
	global_load_dwordx4 v[116:119], v[168:169], off offset:3072
	global_load_dwordx4 v[120:123], v[170:171], off
	global_load_dwordx4 v[124:127], v[170:171], off offset:1024
	global_load_dwordx4 v[128:131], v[170:171], off offset:2048
	global_load_dwordx4 v[132:135], v[170:171], off offset:3072
